# weights region shifted by 1KB (de-alias B rows vs A rows in cache index)
# speedup vs baseline: 1.0150x; 1.0150x over previous
.LBB0_6:
	s_or_b64 exec, exec, s[6:7]
	s_load_dwordx16 s[16:31], s[0:1], 0x0
	s_lshl_b32 s2, s74, 3
	s_ashr_i32 s60, s58, 6
	v_writelane_b32 v254, s2, 6
	v_and_b32_e32 v56, 63, v1
	s_add_i32 s93, s60, s2
	v_writelane_b32 v254, s52, 7
	s_lshl_b32 s61, s52, 3
	s_cmpk_gt_i32 s93, 0x4eff
	v_writelane_b32 v254, s53, 8
	v_lshlrev_b32_e32 v2, 3, v56
	s_cbranch_scc1 .LBB0_357
	s_load_dwordx8 s[36:43], s[0:1], 0x70
	s_lshl_b32 s2, s60, 14
	s_add_i32 s2, s2, 0
	v_lshrrev_b32_e32 v3, 5, v56
	v_and_b32_e32 v4, 31, v1
	v_lshlrev_b32_e32 v8, 2, v4
	v_mul_u32_u24_e32 v9, 0x84, v3
	s_mov_b64 s[6:7], 0x400400
	s_waitcnt lgkmcnt(0)
	s_cmp_lg_u64 s[28:29], 0
	v_add3_u32 v14, s2, v8, v9
	v_lshrrev_b32_e32 v15, 3, v56
	v_and_b32_e32 v8, 56, v2
	v_lshl_add_u64 v[6:7], v[6:7], 0, s[6:7]
	s_cselect_b64 s[6:7], -1, 0
	s_cmp_lg_u64 s[38:39], 0
	v_mul_u32_u24_e32 v9, 0x84, v8
	v_lshlrev_b32_e32 v10, 2, v15
	s_cselect_b64 s[14:15], -1, 0
	s_cmp_lg_u64 s[20:21], 0
	v_add3_u32 v16, s2, v9, v10
	v_writelane_b32 v254, s6, 9
	s_cselect_b64 s[44:45], -1, 0
	s_lshl_b32 s2, s93, 1
	v_mov_b32_e32 v5, 0
	v_or_b32_e32 v17, 8, v15
	v_or_b32_e32 v18, 16, v15
	v_or_b32_e32 v19, 24, v15
	v_writelane_b32 v254, s7, 10
	s_lshl_b32 s62, s93, 5
	s_lshl_b32 s63, s61, 5
	s_add_i32 s64, s2, 0x1ea00
	s_lshl_b32 s65, s61, 1
	v_mov_b32_e32 v20, 0x2780000
	s_movk_i32 s75, 0x2000
	s_movk_i32 s67, 0x4000
	s_mov_b32 s73, 0x10000
	s_mov_b32 s76, 0x12000
	s_mov_b32 s78, 0x16000
	s_mov_b32 s85, 0x24000
	s_mov_b32 s86, 0x26000
	s_mov_b32 s87, 0x28000
	s_mov_b32 s89, 0x2c000
	s_mov_b32 s94, 0x36000
	s_mov_b32 s96, 0x3a000
	s_mov_b32 s97, 0x3c000
	s_mov_b32 s48, 0x3e000
	s_mov_b32 s49, 0x1b000
	v_lshlrev_b32_e32 v4, 2, v4
	v_add_u32_e32 v21, 0x400, v14
	v_add_u32_e32 v22, 0x800, v14
	v_add_u32_e32 v23, 0xc00, v14
	v_add_u32_e32 v24, 0x1000, v14
	v_add_u32_e32 v25, 0x1400, v14
	v_add_u32_e32 v26, 0x1800, v14
	v_add_u32_e32 v27, 0x1c00, v14
	v_lshlrev_b32_e32 v8, 1, v8
	s_mov_b32 s8, 0x31000
	s_mov_b32 s9, 0x63000
	s_mov_b32 s50, 0x79000
	s_mov_b32 s51, 0x7e000
	s_movk_i32 s12, 0x2c00
	s_movk_i32 s13, 0x5000
	s_mov_b32 s66, 0xb000
	s_mov_b32 s68, 0x21000
	s_mov_b32 s69, 0x37000
	s_mov_b32 s70, 0x42000
	s_mov_b32 s71, 0x47000
	s_mov_b32 s72, 0x4d000
	s_mov_b32 s77, 0x52000
	s_mov_b32 s79, 0x58000
	s_mov_b32 s80, 0x5d000
	s_mov_b32 s81, 0x68000
	s_mov_b32 s82, 0x6e000
	s_mov_b32 s83, 0x73000
	s_mov_b32 s84, 0x84000
	s_mov_b32 s88, 0x89000
	s_mov_b32 s90, 0x8f000
	s_mov_b32 s91, 0x94000
	s_mov_b32 s92, 0x9a000
	s_mov_b32 s59, s93
	s_mov_b32 s47, 0
	s_branch .LBB0_10

.LBB0_469:
	s_or_b64 exec, exec, s[0:1]
	v_readlane_b32 s12, v254, 0
	v_readlane_b32 s14, v254, 2
	v_readlane_b32 s15, v254, 3
	s_add_u32 s84, s14, 0x5400000
	s_addc_u32 s85, s15, 0
	s_add_u32 s66, s14, 0x9400000
	s_addc_u32 s67, s15, 0
	s_add_u32 s68, s14, 0x14400000
	s_addc_u32 s69, s15, 0
	s_add_u32 s0, s14, 0x18400000
	s_addc_u32 s1, s15, 0
	v_readlane_b32 s13, v254, 1
	v_writelane_b32 v254, s0, 12
	v_lshl_add_u64 v[0:1], v[0:1], 2, s[10:11]
	s_movk_i32 s79, 0x161
	v_writelane_b32 v254, s1, 13
	s_add_u32 s0, s14, 0x10200
	s_addc_u32 s1, s15, 0
	v_writelane_b32 v254, s0, 14
	s_movk_i32 s3, 0x91
	v_mbcnt_hi_u32_b32 v241, -1, v57
	v_writelane_b32 v254, s1, 15
	s_mov_b64 s[0:1], 0x1400
	v_lshl_add_u64 v[178:179], v[0:1], 0, s[0:1]
	s_mov_b64 s[0:1], 0x2400
	v_lshl_add_u64 v[176:177], v[0:1], 0, s[0:1]
	s_add_u32 s0, s14, 0x13400
	s_addc_u32 s1, s15, 0
	v_writelane_b32 v254, s0, 16
	v_and_b32_e32 v0, 64, v241
	s_mov_b32 s71, 1
	v_writelane_b32 v254, s1, 17
	s_add_u32 s0, s14, 0x13500
	s_addc_u32 s1, s15, 0
	s_add_u32 s58, s14, 0x400400
	s_addc_u32 s61, s15, 0
	s_ashr_i32 s70, s56, 31
	s_ashr_i32 s75, s74, 31
	v_writelane_b32 v254, s0, 18
	s_cmpk_lt_i32 s74, 0xb00
	v_mov_b32_e32 v1, 0
	v_writelane_b32 v254, s1, 19
	s_cselect_b64 s[0:1], -1, 0
	v_writelane_b32 v254, s0, 20
	v_mov_b32_e32 v244, 1
	v_mov_b32_e32 v245, 0x358637bd
	v_writelane_b32 v254, s1, 21
	s_lshr_b32 s0, s75, 29
	s_add_i32 s0, s74, s0
	s_ashr_i32 s4, s0, 3
	s_and_b32 s0, s0, -8
	s_sub_i32 s5, s74, s0
	s_cmpk_lt_i32 s74, 0x480
	s_cselect_b64 s[0:1], -1, 0
	s_add_u32 s72, s14, 0x100000
	v_writelane_b32 v254, s0, 22
	s_addc_u32 s73, s15, 0
	s_mov_b32 s12, 0xf800000
	v_writelane_b32 v254, s1, 23
	s_add_u32 s0, s14, 0x300000
	v_writelane_b32 v254, s0, 24
	s_addc_u32 s0, s15, 0
	s_cmpk_lt_i32 s74, 0x200
	v_writelane_b32 v254, s0, 25
	s_cselect_b64 s[0:1], -1, 0
	s_lshl_b32 s2, s5, 6
	v_writelane_b32 v254, s0, 26
	s_cmpk_lt_i32 s74, 0xa00
	v_mov_b32_e32 v246, 0x260
	v_writelane_b32 v254, s1, 27
	s_cselect_b64 s[0:1], -1, 0
	v_writelane_b32 v254, s0, 28
	s_movk_i32 s81, 0x4000
	s_movk_i32 s76, 0x1200
	v_writelane_b32 v254, s1, 29
	s_and_b64 s[0:1], s[62:63], exec
	s_cselect_b32 s77, 4, 1
	s_add_u32 s0, s14, 0x380000
	v_writelane_b32 v254, s0, 30
	s_addc_u32 s0, s15, 0
	v_writelane_b32 v254, s0, 31
	s_and_b64 s[0:1], s[62:63], exec
	s_cselect_b32 s80, 2, 1
	s_cmp_lt_i32 s5, 0
	s_cselect_b32 s1, s79, 0x160
	s_mul_i32 s0, s5, 0x41
	s_mul_i32 s1, s5, s1
	s_cselect_b32 s6, s3, 0x90
	s_cselect_b32 s7, s0, s2
	s_add_i32 s1, s1, s4
	s_mul_hi_i32 s0, s1, 0x2e8ba2e9
	s_lshr_b32 s2, s0, 31
	s_ashr_i32 s0, s0, 5
	s_add_i32 s0, s0, s2
	s_mul_i32 s2, s0, 0xb0
	s_sub_i32 s1, s1, s2
	s_lshl_b32 s3, s0, 3
	s_bfe_u32 s0, s1, 0x3001c
	s_add_i32 s2, s1, s0
	s_sext_i32_i16 s8, s2
	s_and_b32 s2, s2, 0xfff8
	s_sub_i32 s1, s1, s2
	s_sext_i32_i16 s1, s1
	s_add_i32 s10, s3, s1
	s_ashr_i32 s1, s8, 3
	s_lshr_b32 s0, s8, 3
	v_writelane_b32 v254, s1, 32
	s_mov_b32 s2, s10
	v_writelane_b32 v254, s2, 33
	s_bfe_i64 s[0:1], s[0:1], 0x100000
	s_ashr_i32 s11, s10, 31
	v_writelane_b32 v254, s3, 34
	s_lshl_b64 s[0:1], s[0:1], 19
	s_lshl_b64 s[2:3], s[10:11], 19
	v_writelane_b32 v254, s0, 35
	v_mov_b32_e32 v247, 0x3727c5ac
	v_xor_b32_e32 v243, 1, v241
	v_writelane_b32 v254, s1, 36
	s_add_u32 s0, s84, s2
	s_addc_u32 s1, s85, s3
	s_add_u32 s2, s0, 0x40000
	v_writelane_b32 v254, s0, 37
	s_addc_u32 s3, s1, 0
	v_add_u32_e32 v242, 64, v0
	v_writelane_b32 v254, s1, 38
	s_mul_i32 s0, s5, s6
	s_add_i32 s0, s0, s4
	v_writelane_b32 v254, s2, 39
	s_mul_hi_i32 s1, s0, 0x38e38e39
	v_mov_b32_e32 v248, 0x1200
	v_writelane_b32 v254, s3, 40
	s_lshr_b32 s2, s1, 31
	s_ashr_i32 s1, s1, 4
	s_add_i32 s1, s1, s2
	s_mul_i32 s2, s1, 0x48
	s_sub_i32 s2, s0, s2
	s_bfe_i32 s0, s2, 0x80000
	s_bfe_u32 s0, s0, 0x3000c
	s_add_i32 s3, s2, s0
	s_bfe_i32 s0, s3, 0x80000
	s_and_b32 s3, s3, 0xf8
	s_sub_i32 s2, s2, s3
	s_lshl_b32 s1, s1, 3
	s_sext_i32_i16 s5, s0
	s_sext_i32_i8 s2, s2
	s_add_i32 s6, s1, s2
	s_ashr_i32 s1, s5, 3
	v_writelane_b32 v254, s1, 41
	s_add_i32 s1, s7, s4
	s_ashr_i32 s2, s1, 31
	s_lshr_b32 s2, s2, 27
	s_add_i32 s2, s1, s2
	s_ashr_i32 s3, s2, 5
	s_and_b32 s2, s2, 0xffe0
	s_sub_i32 s1, s1, s2
	s_bfe_i32 s2, s1, 0x80000
	s_bfe_u32 s2, s2, 0x3000c
	s_add_i32 s4, s1, s2
	s_bfe_i32 s2, s4, 0x80000
	s_and_b32 s4, s4, 0xf8
	s_sub_i32 s1, s1, s4
	s_lshl_b32 s3, s3, 3
	s_sext_i32_i8 s1, s1
	s_lshr_b32 s0, s5, 3
	s_sext_i32_i16 s5, s2
	s_add_i32 s1, s3, s1
	v_writelane_b32 v254, s1, 42
	s_ashr_i32 s1, s5, 3
	v_writelane_b32 v254, s1, 43
	s_mov_b32 s4, s6
	s_lshr_b32 s2, s5, 3
	v_writelane_b32 v254, s4, 44
	s_bfe_i64 s[0:1], s[0:1], 0x100000
	s_ashr_i32 s7, s6, 31
	v_writelane_b32 v254, s5, 45
	s_lshl_b64 s[0:1], s[0:1], 19
	s_lshl_b64 s[4:5], s[6:7], 19
	v_writelane_b32 v254, s0, 46
	v_mov_b32_e32 v16, 0xff800000
	v_mov_b64_e32 v[180:181], 0xaff
	v_writelane_b32 v254, s1, 47
	s_add_u32 s0, s84, s4
	s_addc_u32 s1, s85, s5
	s_add_u32 s4, s0, 0x40000
	v_writelane_b32 v254, s0, 48
	s_addc_u32 s5, s1, 0
	s_lshl_b32 s33, s33, 8
	v_writelane_b32 v254, s1, 49
	v_writelane_b32 v254, s4, 50
	s_bfe_i64 s[0:1], s[2:3], 0x100000
	s_add_u32 s82, s14, 0x10400
	v_writelane_b32 v254, s5, 51
	v_writelane_b32 v254, s0, 52
	s_addc_u32 s83, s15, 0
	s_mov_b32 s54, 0xff800000
	v_writelane_b32 v254, s1, 53
	s_add_i32 s0, 0, 0x20200
	v_writelane_b32 v254, s0, 54
	s_add_i32 s0, 0, 0x20204
	v_writelane_b32 v254, s0, 55
	s_add_i32 s0, 0, 0x207d0
	v_writelane_b32 v254, s0, 56
	s_add_i32 s0, 0, 0x207e0
	v_writelane_b32 v254, s0, 57
	s_add_i32 s0, 0, 0x20450
	v_writelane_b32 v254, s0, 58
	s_add_i32 s0, 0, 0x20458
	v_writelane_b32 v254, s0, 59
	s_add_i32 s0, 0, 0x20460
	v_writelane_b32 v254, s0, 60
	s_add_i32 s0, 0, 0x20468
	v_writelane_b32 v254, s0, 61
	s_add_i32 s0, 0, 0x20448
	v_writelane_b32 v254, s0, 62
	s_add_i32 s0, 0, 0x1e00
	v_writelane_b32 v254, s0, 63
	s_add_i32 s0, 0, 0x1e10
	v_writelane_b32 v255, s0, 0
	s_add_i32 s0, 0, 0x1e20
	v_writelane_b32 v255, s0, 1
	s_add_i32 s0, 0, 0x1e30
	v_writelane_b32 v255, s0, 2
	v_writelane_b32 v255, s74, 3
	s_movk_i32 s86, 0x201
	s_movk_i32 s97, 0x81
	v_writelane_b32 v255, s75, 4
	v_writelane_b32 v255, s55, 5
	v_writelane_b32 v255, s59, 6
	v_writelane_b32 v255, s60, 7
	v_writelane_b32 v255, s62, 8
	s_movk_i32 s78, 0x1600
	s_mov_b32 s89, 0
	v_writelane_b32 v255, s63, 9
	v_writelane_b32 v255, s64, 10
	s_mov_b64 s[92:93], 0x80
	s_mov_b64 s[90:91], 0xe00
	v_writelane_b32 v255, s65, 11
	v_writelane_b32 v255, s57, 12
	v_writelane_b32 v255, s66, 13
	s_barrier
	s_nop 0
	v_writelane_b32 v255, s67, 14
	v_writelane_b32 v255, s68, 15
	s_nop 1
	v_writelane_b32 v255, s69, 16
	v_writelane_b32 v255, s58, 17
	v_writelane_b32 v255, s61, 18
	v_writelane_b32 v255, s70, 19
	v_writelane_b32 v255, s72, 20
	s_nop 1
	v_writelane_b32 v255, s73, 21
	v_writelane_b32 v255, s77, 22
	v_writelane_b32 v255, s80, 23
	s_branch .LBB0_472
